# v53: the one invalidate needed after UP (H reuses SLAB_WO addresses) is executed only by the workgroups that touched those lines (WGs 0..63: WO slice owners and LN1 sample rows)
# speedup vs baseline: 1.0140x; 1.0140x over previous
; __device__ __forceinline__ unsigned xb_ld(unsigned* p)              { return __hip_atomic_load(p, __ATOMIC_RELAXED, __HIP_MEMORY_SCOPE_AGENT); }
; __device__ __forceinline__ unsigned xb_add(unsigned* p, unsigned v) { return __hip_atomic_fetch_add(p, v, __ATOMIC_RELAXED, __HIP_MEMORY_SCOPE_AGENT); }
; #define XB_SPIN(cond, bar) do { unsigned _sp = 0; while (cond) { __builtin_amdgcn_s_sleep(1); \
;     if ((++_sp & 255u) == 0u) { if (xb_ld(&(bar)[XB_TMO])) break; if (_sp > XB_SPIN_CAP) { atomicAdd(&(bar)[XB_TMO], 1u); break; } } } } while (0)
; __device__ __forceinline__ void xcd_barrier(const XcdBarrier& b) {
;     ...
;             else XB_SPIN(xb_ld(&bar[XB_TOPGEN]) == tg, bar);
;             __builtin_amdgcn_fence(__ATOMIC_ACQUIRE, "agent");
;             xb_add(&bar[XB_XGEN(b.x)], 1u);
;             asm volatile("s_waitcnt vmcnt(0)" ::: "memory");
;         } else {
;             XB_SPIN(xb_ld(&bar[XB_XGEN(b.x)]) == gen, bar);
;             __builtin_amdgcn_fence(__ATOMIC_ACQUIRE, "agent");
;             asm volatile("s_waitcnt vmcnt(0)" ::: "memory");
.Lfb7_done:
	s_cmp_lg_u32 s33, 0x100
	s_cbranch_scc1 .Lfb7_doinv
	v_readlane_b32 s3, v244, 33
	s_nop 3
	s_cmp_lt_u32 s3, 64
	s_cbranch_scc0 .Lfb7_noinv
.Lfb7_doinv:
	buffer_inv sc1
.Lfb7_noinv:
	s_waitcnt vmcnt(0)
